# P7 fused: both branch GEMMs accumulate in one pass (acc*=Ga/max(Gb,2^-60), final *max(Gb,2^-60)); removes MG write+readback and second GEMM restart
# speedup vs baseline: 1.0083x; 1.0083x over previous
.LBB0_1055:
	s_add_i32 s52, s52, 1
	s_cmp_eq_u32 s52, 1
	s_cbranch_scc1 .Lp7_force_next
	s_mul_i32 s2, s52, s57
	s_mul_hi_u32 s3, s52, s79
	s_add_i32 s3, s3, s2
	s_mul_i32 s2, s52, s79
	s_add_u32 s2, s2, s82
	s_addc_u32 s3, s3, s9
	v_cmp_gt_i64_e32 vcc, s[2:3], v[142:143]
	v_cmp_lt_i64_e64 s[4:5], s[2:3], v[140:141]
	s_cbranch_vccnz .LBB0_1061
	s_ashr_i32 s3, s2, 31
	s_lshr_b32 s3, s3, 29
	s_add_i32 s28, s2, s3
	s_and_b32 s3, s28, -8
	s_sub_i32 s29, s2, s3
	s_cmp_gt_i32 s29, -1
	s_mov_b64 s[2:3], -1
	s_cbranch_scc0 .LBB0_1058
	s_lshl_b32 s30, s29, 5
	s_mov_b64 s[2:3], 0

.LBB0_1063:
	s_ashr_i32 s29, s28, 31
	s_lshl_b64 s[34:35], s[28:29], 18
	s_add_u32 s34, s45, s34
	s_addc_u32 s35, s46, s35
	s_cmp_lg_u32 s52, 1
	s_cbranch_scc1 .Lp7_noadj
	s_sub_u32 s34, s34, 0x1000000
	s_subb_u32 s35, s35, 0
	s_add_u32 s30, s30, 0x100000
	s_addc_u32 s31, s31, 0
.Lp7_noadj:
	s_andn2_b64 vcc, exec, s[24:25]
	s_cbranch_vccnz .LBB0_1066
	s_and_b64 s[4:5], s[4:5], exec
	s_cselect_b32 s29, s35, s39
	s_cselect_b32 s62, s34, s38
	s_add_u32 s63, s0, 0x100
	s_addc_u32 s64, s1, 0
	s_add_u32 s0, s38, 0x20080
	s_addc_u32 s1, s39, 0
	s_mov_b32 s4, 0

.LBB0_1068:
	s_cmp_eq_u32 s52, 1
	s_cbranch_scc1 .Lp7_scale
	v_lshl_add_u32 v146, s36, 8, v151
	v_lshl_add_u32 v144, s61, 8, v153
	v_ashrrev_i32_e32 v147, 31, v146
	v_ashrrev_i32_e32 v145, 31, v144
	v_lshlrev_b64 v[148:149], 12, v[146:147]
	v_lshl_add_u64 v[148:149], s[20:21], 0, v[148:149]
	v_lshlrev_b64 v[144:145], 1, v[144:145]
	v_or_b32_e32 v176, 16, v146
	v_lshl_add_u64 v[148:149], v[148:149], 0, v[144:145]
	v_ashrrev_i32_e32 v177, 31, v176
	global_load_dwordx4 v[156:159], v[148:149], off offset:2048
	global_load_dwordx4 v[160:163], v[148:149], off offset:2304
	v_lshlrev_b64 v[148:149], 12, v[176:177]
	v_lshl_add_u64 v[148:149], s[20:21], 0, v[148:149]
	v_lshl_add_u64 v[148:149], v[148:149], 0, v[144:145]
	v_or_b32_e32 v184, 32, v146
	global_load_dwordx4 v[164:167], v[148:149], off offset:2048
	global_load_dwordx4 v[168:171], v[148:149], off offset:2304
	v_ashrrev_i32_e32 v185, 31, v184
	v_lshlrev_b64 v[172:173], 11, v[146:147]
	v_lshlrev_b64 v[174:175], 12, v[184:185]
	v_lshl_add_u64 v[180:181], s[18:19], 0, v[172:173]
	v_lshl_add_u64 v[172:173], s[20:21], 0, v[174:175]
	v_lshl_add_u64 v[182:183], v[172:173], 0, v[144:145]
	global_load_dwordx4 v[172:175], v[182:183], off offset:2048
	v_or_b32_e32 v148, 48, v146
	v_ashrrev_i32_e32 v149, 31, v148
	v_lshlrev_b64 v[178:179], 12, v[148:149]
	v_lshlrev_b64 v[176:177], 11, v[176:177]
	v_lshl_add_u64 v[178:179], s[20:21], 0, v[178:179]
	v_lshl_add_u64 v[176:177], s[18:19], 0, v[176:177]
	v_lshl_add_u64 v[188:189], v[178:179], 0, v[144:145]
	v_lshl_add_u64 v[192:193], v[180:181], 0, v[144:145]
	v_lshl_add_u64 v[194:195], v[176:177], 0, v[144:145]
	global_load_dwordx4 v[176:179], v[182:183], off offset:2304
	s_nop 0
	global_load_dwordx4 v[180:183], v[188:189], off offset:2048
	s_nop 0
	global_load_dwordx4 v[188:191], v[188:189], off offset:2304
	s_and_b64 vcc, exec, s[2:3]
	s_mov_b64 s[0:1], -1
	s_waitcnt vmcnt(0)
	v_lshlrev_b32_e32 v196, 16, v156
	v_max_f32_e32 v196, 0x21800000, v196
	v_and_b32_e32 v197, 0xffff0000, v156
	v_max_f32_e32 v197, 0x21800000, v197
	v_lshlrev_b32_e32 v156, 16, v157
	v_max_f32_e32 v156, 0x21800000, v156
	v_and_b32_e32 v157, 0xffff0000, v157
	v_max_f32_e32 v157, 0x21800000, v157
	v_lshlrev_b32_e32 v198, 16, v158
	v_max_f32_e32 v198, 0x21800000, v198
	v_and_b32_e32 v199, 0xffff0000, v158
	v_max_f32_e32 v199, 0x21800000, v199
	v_lshlrev_b32_e32 v158, 16, v159
	v_max_f32_e32 v158, 0x21800000, v158
	v_and_b32_e32 v159, 0xffff0000, v159
	v_max_f32_e32 v159, 0x21800000, v159
	v_lshlrev_b32_e32 v200, 16, v160
	v_max_f32_e32 v200, 0x21800000, v200
	v_and_b32_e32 v201, 0xffff0000, v160
	v_max_f32_e32 v201, 0x21800000, v201
	v_lshlrev_b32_e32 v160, 16, v161
	v_max_f32_e32 v160, 0x21800000, v160
	v_and_b32_e32 v161, 0xffff0000, v161
	v_max_f32_e32 v161, 0x21800000, v161
	v_lshlrev_b32_e32 v202, 16, v162
	v_max_f32_e32 v202, 0x21800000, v202
	v_and_b32_e32 v203, 0xffff0000, v162
	v_max_f32_e32 v203, 0x21800000, v203
	v_lshlrev_b32_e32 v162, 16, v163
	v_max_f32_e32 v162, 0x21800000, v162
	v_and_b32_e32 v163, 0xffff0000, v163
	v_max_f32_e32 v163, 0x21800000, v163
	v_pk_mul_f32 v[110:111], v[110:111], v[156:157]
	v_pk_mul_f32 v[108:109], v[108:109], v[196:197]
	v_pk_mul_f32 v[114:115], v[114:115], v[158:159]
	v_pk_mul_f32 v[112:113], v[112:113], v[198:199]
	v_lshlrev_b32_e32 v156, 16, v164
	v_max_f32_e32 v156, 0x21800000, v156
	v_and_b32_e32 v157, 0xffff0000, v164
	v_max_f32_e32 v157, 0x21800000, v157
	v_lshlrev_b32_e32 v158, 16, v165
	v_max_f32_e32 v158, 0x21800000, v158
	v_and_b32_e32 v159, 0xffff0000, v165
	v_max_f32_e32 v159, 0x21800000, v159
	v_pk_mul_f32 v[122:123], v[122:123], v[160:161]
	v_pk_mul_f32 v[120:121], v[120:121], v[200:201]
	v_pk_mul_f32 v[126:127], v[126:127], v[162:163]
	v_pk_mul_f32 v[124:125], v[124:125], v[202:203]
	v_lshlrev_b32_e32 v160, 16, v166
	v_max_f32_e32 v160, 0x21800000, v160
	v_and_b32_e32 v161, 0xffff0000, v166
	v_max_f32_e32 v161, 0x21800000, v161
	v_lshlrev_b32_e32 v162, 16, v167
	v_max_f32_e32 v162, 0x21800000, v162
	v_and_b32_e32 v163, 0xffff0000, v167
	v_max_f32_e32 v163, 0x21800000, v163
	v_cvt_pk_bf16_f32 v108, v108, v109
	v_cvt_pk_bf16_f32 v109, v110, v111
	v_cvt_pk_bf16_f32 v110, v112, v113
	v_cvt_pk_bf16_f32 v111, v114, v115
	v_pk_mul_f32 v[112:113], v[98:99], v[158:159]
	v_pk_mul_f32 v[114:115], v[96:97], v[156:157]
	global_store_dwordx4 v[192:193], v[108:111], off
	v_cvt_pk_bf16_f32 v96, v120, v121
	v_cvt_pk_bf16_f32 v97, v122, v123
	v_cvt_pk_bf16_f32 v98, v124, v125
	v_cvt_pk_bf16_f32 v99, v126, v127
	v_lshlrev_b32_e32 v164, 16, v168
	v_max_f32_e32 v164, 0x21800000, v164
	v_and_b32_e32 v165, 0xffff0000, v168
	v_max_f32_e32 v165, 0x21800000, v165
	v_lshlrev_b32_e32 v166, 16, v169
	v_max_f32_e32 v166, 0x21800000, v166
	v_pk_mul_f32 v[102:103], v[102:103], v[162:163]
	v_pk_mul_f32 v[100:101], v[100:101], v[160:161]
	global_store_dwordx4 v[192:193], v[96:99], off offset:256
	v_and_b32_e32 v167, 0xffff0000, v169
	v_max_f32_e32 v167, 0x21800000, v167
	s_nop 0
	v_cvt_pk_bf16_f32 v96, v114, v115
	v_cvt_pk_bf16_f32 v97, v112, v113
	v_cvt_pk_bf16_f32 v98, v100, v101
	v_cvt_pk_bf16_f32 v99, v102, v103
	global_store_dwordx4 v[194:195], v[96:99], off
	v_lshlrev_b32_e32 v100, 16, v170
	v_max_f32_e32 v100, 0x21800000, v100
	v_and_b32_e32 v101, 0xffff0000, v170
	v_max_f32_e32 v101, 0x21800000, v101
	v_pk_mul_f32 v[98:99], v[118:119], v[166:167]
	v_pk_mul_f32 v[96:97], v[116:117], v[164:165]
	v_lshlrev_b32_e32 v102, 16, v171
	v_max_f32_e32 v102, 0x21800000, v102
	v_and_b32_e32 v103, 0xffff0000, v171
	v_max_f32_e32 v103, 0x21800000, v103
	v_pk_mul_f32 v[102:103], v[106:107], v[102:103]
	v_pk_mul_f32 v[100:101], v[104:105], v[100:101]
	v_cvt_pk_bf16_f32 v96, v96, v97
	v_cvt_pk_bf16_f32 v97, v98, v99
	s_nop 0
	v_cvt_pk_bf16_f32 v98, v100, v101
	v_cvt_pk_bf16_f32 v99, v102, v103
	global_store_dwordx4 v[194:195], v[96:99], off offset:256
	v_lshlrev_b32_e32 v100, 16, v173
	v_max_f32_e32 v100, 0x21800000, v100
	v_and_b32_e32 v101, 0xffff0000, v173
	v_max_f32_e32 v101, 0x21800000, v101
	v_lshlrev_b32_e32 v98, 16, v172
	v_max_f32_e32 v98, 0x21800000, v98
	v_and_b32_e32 v99, 0xffff0000, v172
	v_max_f32_e32 v99, 0x21800000, v99
	v_lshlrev_b64 v[96:97], 11, v[184:185]
	v_pk_mul_f32 v[94:95], v[94:95], v[100:101]
	v_pk_mul_f32 v[92:93], v[92:93], v[98:99]
	v_lshlrev_b32_e32 v98, 16, v174
	v_max_f32_e32 v98, 0x21800000, v98
	v_and_b32_e32 v99, 0xffff0000, v174
	v_max_f32_e32 v99, 0x21800000, v99
	v_lshlrev_b32_e32 v100, 16, v175
	v_max_f32_e32 v100, 0x21800000, v100
	v_and_b32_e32 v101, 0xffff0000, v175
	v_max_f32_e32 v101, 0x21800000, v101
	v_lshl_add_u64 v[96:97], s[18:19], 0, v[96:97]
	v_pk_mul_f32 v[100:101], v[86:87], v[100:101]
	v_pk_mul_f32 v[86:87], v[84:85], v[98:99]
	v_cvt_pk_bf16_f32 v84, v92, v93
	v_cvt_pk_bf16_f32 v85, v94, v95
	v_lshl_add_u64 v[92:93], v[96:97], 0, v[144:145]
	v_cvt_pk_bf16_f32 v86, v86, v87
	v_cvt_pk_bf16_f32 v87, v100, v101
	global_store_dwordx4 v[92:93], v[84:87], off
	v_add_u32_e32 v98, 0x80, v146
	v_ashrrev_i32_e32 v99, 31, v98
	v_lshlrev_b32_e32 v84, 16, v176
	v_max_f32_e32 v84, 0x21800000, v84
	v_and_b32_e32 v85, 0xffff0000, v176
	v_max_f32_e32 v85, 0x21800000, v85
	v_lshlrev_b32_e32 v86, 16, v177
	v_max_f32_e32 v86, 0x21800000, v86
	v_and_b32_e32 v87, 0xffff0000, v177
	v_max_f32_e32 v87, 0x21800000, v87
	v_pk_mul_f32 v[86:87], v[90:91], v[86:87]
	v_pk_mul_f32 v[84:85], v[88:89], v[84:85]
	v_lshlrev_b32_e32 v88, 16, v178
	v_max_f32_e32 v88, 0x21800000, v88
	v_and_b32_e32 v89, 0xffff0000, v178
	v_max_f32_e32 v89, 0x21800000, v89
	v_lshlrev_b32_e32 v90, 16, v179
	v_max_f32_e32 v90, 0x21800000, v90
	v_and_b32_e32 v91, 0xffff0000, v179
	v_max_f32_e32 v91, 0x21800000, v91
	v_pk_mul_f32 v[90:91], v[82:83], v[90:91]
	v_pk_mul_f32 v[82:83], v[80:81], v[88:89]
	v_cvt_pk_bf16_f32 v80, v84, v85
	v_cvt_pk_bf16_f32 v81, v86, v87
	v_lshlrev_b32_e32 v84, 16, v181
	v_max_f32_e32 v84, 0x21800000, v84
	v_cvt_pk_bf16_f32 v82, v82, v83
	v_cvt_pk_bf16_f32 v83, v90, v91
	global_store_dwordx4 v[92:93], v[80:83], off offset:256
	v_and_b32_e32 v85, 0xffff0000, v181
	v_max_f32_e32 v85, 0x21800000, v85
	v_pk_mul_f32 v[78:79], v[78:79], v[84:85]
	v_lshlrev_b32_e32 v82, 16, v180
	v_max_f32_e32 v82, 0x21800000, v82
	v_and_b32_e32 v83, 0xffff0000, v180
	v_max_f32_e32 v83, 0x21800000, v83
	v_lshlrev_b64 v[80:81], 11, v[148:149]
	v_pk_mul_f32 v[76:77], v[76:77], v[82:83]
	v_lshlrev_b32_e32 v82, 16, v182
	v_max_f32_e32 v82, 0x21800000, v82
	v_and_b32_e32 v83, 0xffff0000, v182
	v_max_f32_e32 v83, 0x21800000, v83
	v_lshlrev_b32_e32 v84, 16, v183
	v_max_f32_e32 v84, 0x21800000, v84
	v_and_b32_e32 v85, 0xffff0000, v183
	v_max_f32_e32 v85, 0x21800000, v85
	v_lshl_add_u64 v[80:81], s[18:19], 0, v[80:81]
	v_pk_mul_f32 v[84:85], v[70:71], v[84:85]
	v_pk_mul_f32 v[70:71], v[68:69], v[82:83]
	v_cvt_pk_bf16_f32 v68, v76, v77
	v_cvt_pk_bf16_f32 v69, v78, v79
	v_lshl_add_u64 v[78:79], v[80:81], 0, v[144:145]
	v_cvt_pk_bf16_f32 v70, v70, v71
	v_cvt_pk_bf16_f32 v71, v84, v85
	global_store_dwordx4 v[78:79], v[68:71], off
	v_add_u32_e32 v100, 0x90, v146
	v_ashrrev_i32_e32 v101, 31, v100
	v_lshlrev_b32_e32 v68, 16, v188
	v_max_f32_e32 v68, 0x21800000, v68
	v_and_b32_e32 v69, 0xffff0000, v188
	v_max_f32_e32 v69, 0x21800000, v69
	v_lshlrev_b32_e32 v70, 16, v189
	v_max_f32_e32 v70, 0x21800000, v70
	v_and_b32_e32 v71, 0xffff0000, v189
	v_max_f32_e32 v71, 0x21800000, v71
	v_pk_mul_f32 v[70:71], v[74:75], v[70:71]
	v_pk_mul_f32 v[68:69], v[72:73], v[68:69]
	v_lshlrev_b32_e32 v72, 16, v190
	v_max_f32_e32 v72, 0x21800000, v72
	v_and_b32_e32 v73, 0xffff0000, v190
	v_max_f32_e32 v73, 0x21800000, v73
	v_lshlrev_b32_e32 v74, 16, v191
	v_max_f32_e32 v74, 0x21800000, v74
	v_and_b32_e32 v75, 0xffff0000, v191
	v_max_f32_e32 v75, 0x21800000, v75
	v_pk_mul_f32 v[74:75], v[66:67], v[74:75]
	v_pk_mul_f32 v[66:67], v[64:65], v[72:73]
	v_cvt_pk_bf16_f32 v64, v68, v69
	v_lshlrev_b64 v[68:69], 12, v[98:99]
	v_lshl_add_u64 v[68:69], s[20:21], 0, v[68:69]
	v_lshl_add_u64 v[68:69], v[68:69], 0, v[144:145]
	v_cvt_pk_bf16_f32 v65, v70, v71
	v_cvt_pk_bf16_f32 v66, v66, v67
	v_cvt_pk_bf16_f32 v67, v74, v75
	global_load_dwordx4 v[74:77], v[68:69], off offset:2048
	v_add_u32_e32 v102, 0xa0, v146
	global_store_dwordx4 v[78:79], v[64:67], off offset:256
	global_load_dwordx4 v[78:81], v[68:69], off offset:2304
	v_ashrrev_i32_e32 v103, 31, v102
	v_lshlrev_b64 v[64:65], 12, v[100:101]
	v_lshl_add_u64 v[64:65], s[20:21], 0, v[64:65]
	v_lshl_add_u64 v[64:65], v[64:65], 0, v[144:145]
	global_load_dwordx4 v[82:85], v[64:65], off offset:2048
	global_load_dwordx4 v[86:89], v[64:65], off offset:2304
	v_lshlrev_b64 v[64:65], 12, v[102:103]
	v_lshl_add_u64 v[64:65], s[20:21], 0, v[64:65]
	v_lshl_add_u64 v[64:65], v[64:65], 0, v[144:145]
	global_load_dwordx4 v[90:93], v[64:65], off offset:2048
	global_load_dwordx4 v[94:97], v[64:65], off offset:2304
	v_add_u32_e32 v72, 0xb0, v146
	v_ashrrev_i32_e32 v73, 31, v72
	v_lshlrev_b64 v[64:65], 12, v[72:73]
	v_lshl_add_u64 v[64:65], s[20:21], 0, v[64:65]
	v_lshl_add_u64 v[64:65], v[64:65], 0, v[144:145]
	global_load_dwordx4 v[68:71], v[64:65], off offset:2048
	s_nop 0
	global_load_dwordx4 v[64:67], v[64:65], off offset:2304
	v_lshlrev_b64 v[98:99], 11, v[98:99]
	v_lshl_add_u64 v[98:99], s[18:19], 0, v[98:99]
	s_waitcnt vmcnt(0)
	v_lshlrev_b32_e32 v104, 16, v74
	v_max_f32_e32 v104, 0x21800000, v104
	v_and_b32_e32 v105, 0xffff0000, v74
	v_max_f32_e32 v105, 0x21800000, v105
	v_lshlrev_b32_e32 v74, 16, v75
	v_max_f32_e32 v74, 0x21800000, v74
	v_and_b32_e32 v75, 0xffff0000, v75
	v_max_f32_e32 v75, 0x21800000, v75
	v_pk_mul_f32 v[62:63], v[62:63], v[74:75]
	v_lshlrev_b32_e32 v74, 16, v76
	v_max_f32_e32 v74, 0x21800000, v74
	v_and_b32_e32 v75, 0xffff0000, v76
	v_max_f32_e32 v75, 0x21800000, v75
	v_lshlrev_b32_e32 v76, 16, v77
	v_max_f32_e32 v76, 0x21800000, v76
	v_and_b32_e32 v77, 0xffff0000, v77
	v_max_f32_e32 v77, 0x21800000, v77
	v_pk_mul_f32 v[60:61], v[60:61], v[104:105]
	v_pk_mul_f32 v[76:77], v[54:55], v[76:77]
	v_pk_mul_f32 v[54:55], v[52:53], v[74:75]
	v_cvt_pk_bf16_f32 v52, v60, v61
	v_cvt_pk_bf16_f32 v53, v62, v63
	v_lshl_add_u64 v[60:61], v[98:99], 0, v[144:145]
	v_cvt_pk_bf16_f32 v54, v54, v55
	v_cvt_pk_bf16_f32 v55, v76, v77
	global_store_dwordx4 v[60:61], v[52:55], off
	s_nop 1
	v_lshlrev_b32_e32 v52, 16, v78
	v_max_f32_e32 v52, 0x21800000, v52
	v_and_b32_e32 v53, 0xffff0000, v78
	v_max_f32_e32 v53, 0x21800000, v53
	v_lshlrev_b32_e32 v54, 16, v79
	v_max_f32_e32 v54, 0x21800000, v54
	v_and_b32_e32 v55, 0xffff0000, v79
	v_max_f32_e32 v55, 0x21800000, v55
	v_pk_mul_f32 v[54:55], v[58:59], v[54:55]
	v_pk_mul_f32 v[52:53], v[56:57], v[52:53]
	v_lshlrev_b32_e32 v56, 16, v80
	v_max_f32_e32 v56, 0x21800000, v56
	v_and_b32_e32 v57, 0xffff0000, v80
	v_max_f32_e32 v57, 0x21800000, v57
	v_lshlrev_b32_e32 v58, 16, v81
	v_max_f32_e32 v58, 0x21800000, v58
	v_and_b32_e32 v59, 0xffff0000, v81
	v_max_f32_e32 v59, 0x21800000, v59
	v_pk_mul_f32 v[58:59], v[50:51], v[58:59]
	v_pk_mul_f32 v[50:51], v[48:49], v[56:57]
	v_cvt_pk_bf16_f32 v48, v52, v53
	v_cvt_pk_bf16_f32 v49, v54, v55
	v_lshlrev_b32_e32 v52, 16, v83
	v_max_f32_e32 v52, 0x21800000, v52
	v_cvt_pk_bf16_f32 v50, v50, v51
	v_cvt_pk_bf16_f32 v51, v58, v59
	global_store_dwordx4 v[60:61], v[48:51], off offset:256
	v_and_b32_e32 v53, 0xffff0000, v83
	v_max_f32_e32 v53, 0x21800000, v53
	v_pk_mul_f32 v[46:47], v[46:47], v[52:53]
	v_lshlrev_b32_e32 v50, 16, v82
	v_max_f32_e32 v50, 0x21800000, v50
	v_and_b32_e32 v51, 0xffff0000, v82
	v_max_f32_e32 v51, 0x21800000, v51
	v_lshlrev_b64 v[48:49], 11, v[100:101]
	v_pk_mul_f32 v[44:45], v[44:45], v[50:51]
	v_lshlrev_b32_e32 v50, 16, v84
	v_max_f32_e32 v50, 0x21800000, v50
	v_and_b32_e32 v51, 0xffff0000, v84
	v_max_f32_e32 v51, 0x21800000, v51
	v_lshlrev_b32_e32 v52, 16, v85
	v_max_f32_e32 v52, 0x21800000, v52
	v_and_b32_e32 v53, 0xffff0000, v85
	v_max_f32_e32 v53, 0x21800000, v53
	v_lshl_add_u64 v[48:49], s[18:19], 0, v[48:49]
	v_pk_mul_f32 v[52:53], v[38:39], v[52:53]
	v_pk_mul_f32 v[38:39], v[36:37], v[50:51]
	v_cvt_pk_bf16_f32 v36, v44, v45
	v_cvt_pk_bf16_f32 v37, v46, v47
	v_lshl_add_u64 v[44:45], v[48:49], 0, v[144:145]
	v_cvt_pk_bf16_f32 v38, v38, v39
	v_cvt_pk_bf16_f32 v39, v52, v53
	global_store_dwordx4 v[44:45], v[36:39], off
	s_nop 1
	v_lshlrev_b32_e32 v36, 16, v86
	v_max_f32_e32 v36, 0x21800000, v36
	v_and_b32_e32 v37, 0xffff0000, v86
	v_max_f32_e32 v37, 0x21800000, v37
	v_lshlrev_b32_e32 v38, 16, v87
	v_max_f32_e32 v38, 0x21800000, v38
	v_and_b32_e32 v39, 0xffff0000, v87
	v_max_f32_e32 v39, 0x21800000, v39
	v_pk_mul_f32 v[38:39], v[42:43], v[38:39]
	v_pk_mul_f32 v[36:37], v[40:41], v[36:37]
	v_lshlrev_b32_e32 v40, 16, v88
	v_max_f32_e32 v40, 0x21800000, v40
	v_and_b32_e32 v41, 0xffff0000, v88
	v_max_f32_e32 v41, 0x21800000, v41
	v_lshlrev_b32_e32 v42, 16, v89
	v_max_f32_e32 v42, 0x21800000, v42
	v_and_b32_e32 v43, 0xffff0000, v89
	v_max_f32_e32 v43, 0x21800000, v43
	v_pk_mul_f32 v[42:43], v[34:35], v[42:43]
	v_pk_mul_f32 v[34:35], v[32:33], v[40:41]
	v_cvt_pk_bf16_f32 v32, v36, v37
	v_cvt_pk_bf16_f32 v33, v38, v39
	v_lshlrev_b32_e32 v36, 16, v91
	v_max_f32_e32 v36, 0x21800000, v36
	v_cvt_pk_bf16_f32 v34, v34, v35
	v_cvt_pk_bf16_f32 v35, v42, v43
	global_store_dwordx4 v[44:45], v[32:35], off offset:256
	v_and_b32_e32 v37, 0xffff0000, v91
	v_max_f32_e32 v37, 0x21800000, v37
	v_pk_mul_f32 v[30:31], v[30:31], v[36:37]
	v_lshlrev_b32_e32 v34, 16, v90
	v_max_f32_e32 v34, 0x21800000, v34
	v_and_b32_e32 v35, 0xffff0000, v90
	v_max_f32_e32 v35, 0x21800000, v35
	v_lshlrev_b64 v[32:33], 11, v[102:103]
	v_pk_mul_f32 v[28:29], v[28:29], v[34:35]
	v_lshlrev_b32_e32 v34, 16, v92
	v_max_f32_e32 v34, 0x21800000, v34
	v_and_b32_e32 v35, 0xffff0000, v92
	v_max_f32_e32 v35, 0x21800000, v35
	v_lshlrev_b32_e32 v36, 16, v93
	v_max_f32_e32 v36, 0x21800000, v36
	v_and_b32_e32 v37, 0xffff0000, v93
	v_max_f32_e32 v37, 0x21800000, v37
	v_lshl_add_u64 v[32:33], s[18:19], 0, v[32:33]
	v_pk_mul_f32 v[36:37], v[22:23], v[36:37]
	v_pk_mul_f32 v[22:23], v[20:21], v[34:35]
	v_cvt_pk_bf16_f32 v20, v28, v29
	v_cvt_pk_bf16_f32 v21, v30, v31
	v_lshl_add_u64 v[28:29], v[32:33], 0, v[144:145]
	v_cvt_pk_bf16_f32 v22, v22, v23
	v_cvt_pk_bf16_f32 v23, v36, v37
	global_store_dwordx4 v[28:29], v[20:23], off
	s_nop 1
	v_lshlrev_b32_e32 v20, 16, v94
	v_max_f32_e32 v20, 0x21800000, v20
	v_and_b32_e32 v21, 0xffff0000, v94
	v_max_f32_e32 v21, 0x21800000, v21
	v_lshlrev_b32_e32 v22, 16, v95
	v_max_f32_e32 v22, 0x21800000, v22
	v_and_b32_e32 v23, 0xffff0000, v95
	v_max_f32_e32 v23, 0x21800000, v23
	v_pk_mul_f32 v[22:23], v[26:27], v[22:23]
	v_pk_mul_f32 v[20:21], v[24:25], v[20:21]
	v_lshlrev_b32_e32 v24, 16, v96
	v_max_f32_e32 v24, 0x21800000, v24
	v_and_b32_e32 v25, 0xffff0000, v96
	v_max_f32_e32 v25, 0x21800000, v25
	v_lshlrev_b32_e32 v26, 16, v97
	v_max_f32_e32 v26, 0x21800000, v26
	v_and_b32_e32 v27, 0xffff0000, v97
	v_max_f32_e32 v27, 0x21800000, v27
	v_pk_mul_f32 v[26:27], v[18:19], v[26:27]
	v_pk_mul_f32 v[18:19], v[16:17], v[24:25]
	v_cvt_pk_bf16_f32 v16, v20, v21
	v_cvt_pk_bf16_f32 v17, v22, v23
	v_lshlrev_b32_e32 v20, 16, v69
	v_max_f32_e32 v20, 0x21800000, v20
	v_cvt_pk_bf16_f32 v18, v18, v19
	v_cvt_pk_bf16_f32 v19, v26, v27
	global_store_dwordx4 v[28:29], v[16:19], off offset:256
	v_and_b32_e32 v21, 0xffff0000, v69
	v_max_f32_e32 v21, 0x21800000, v21
	v_pk_mul_f32 v[14:15], v[14:15], v[20:21]
	v_lshlrev_b32_e32 v18, 16, v68
	v_max_f32_e32 v18, 0x21800000, v18
	v_and_b32_e32 v19, 0xffff0000, v68
	v_max_f32_e32 v19, 0x21800000, v19
	v_lshlrev_b64 v[16:17], 11, v[72:73]
	v_pk_mul_f32 v[12:13], v[12:13], v[18:19]
	v_lshlrev_b32_e32 v18, 16, v70
	v_max_f32_e32 v18, 0x21800000, v18
	v_and_b32_e32 v19, 0xffff0000, v70
	v_max_f32_e32 v19, 0x21800000, v19
	v_lshlrev_b32_e32 v20, 16, v71
	v_max_f32_e32 v20, 0x21800000, v20
	v_and_b32_e32 v21, 0xffff0000, v71
	v_max_f32_e32 v21, 0x21800000, v21
	v_lshl_add_u64 v[16:17], s[18:19], 0, v[16:17]
	v_pk_mul_f32 v[20:21], v[6:7], v[20:21]
	v_pk_mul_f32 v[6:7], v[4:5], v[18:19]
	v_cvt_pk_bf16_f32 v4, v12, v13
	v_cvt_pk_bf16_f32 v5, v14, v15
	v_lshl_add_u64 v[12:13], v[16:17], 0, v[144:145]
	v_cvt_pk_bf16_f32 v6, v6, v7
	v_cvt_pk_bf16_f32 v7, v20, v21
	global_store_dwordx4 v[12:13], v[4:7], off
	s_nop 1
	v_lshlrev_b32_e32 v4, 16, v64
	v_max_f32_e32 v4, 0x21800000, v4
	v_and_b32_e32 v5, 0xffff0000, v64
	v_max_f32_e32 v5, 0x21800000, v5
	v_lshlrev_b32_e32 v6, 16, v65
	v_max_f32_e32 v6, 0x21800000, v6
	v_and_b32_e32 v7, 0xffff0000, v65
	v_max_f32_e32 v7, 0x21800000, v7
	v_pk_mul_f32 v[6:7], v[10:11], v[6:7]
	v_pk_mul_f32 v[4:5], v[8:9], v[4:5]
	v_lshlrev_b32_e32 v8, 16, v66
	v_max_f32_e32 v8, 0x21800000, v8
	v_and_b32_e32 v9, 0xffff0000, v66
	v_max_f32_e32 v9, 0x21800000, v9
	v_lshlrev_b32_e32 v10, 16, v67
	v_max_f32_e32 v10, 0x21800000, v10
	v_and_b32_e32 v11, 0xffff0000, v67
	v_max_f32_e32 v11, 0x21800000, v11
	v_pk_mul_f32 v[10:11], v[2:3], v[10:11]
	v_pk_mul_f32 v[2:3], v[0:1], v[8:9]
	v_cvt_pk_bf16_f32 v0, v4, v5
	v_cvt_pk_bf16_f32 v1, v6, v7
	s_nop 0
	v_cvt_pk_bf16_f32 v2, v2, v3
	v_cvt_pk_bf16_f32 v3, v10, v11
	global_store_dwordx4 v[12:13], v[0:3], off offset:256
	s_cbranch_vccnz .LBB0_1054
	s_andn2_b64 vcc, exec, s[16:17]
	v_pk_mov_b32 v[108:109], 0, 0
	v_pk_mov_b32 v[110:111], 0, 0
	v_pk_mov_b32 v[112:113], 0, 0
	v_pk_mov_b32 v[114:115], 0, 0
	v_pk_mov_b32 v[96:97], 0, 0
	v_pk_mov_b32 v[98:99], 0, 0
	v_pk_mov_b32 v[100:101], 0, 0
	v_pk_mov_b32 v[102:103], 0, 0
	v_pk_mov_b32 v[92:93], 0, 0
	v_pk_mov_b32 v[94:95], 0, 0
	v_pk_mov_b32 v[84:85], 0, 0
	v_pk_mov_b32 v[86:87], 0, 0
	v_pk_mov_b32 v[76:77], 0, 0
	v_pk_mov_b32 v[78:79], 0, 0
	v_pk_mov_b32 v[68:69], 0, 0
	v_pk_mov_b32 v[70:71], 0, 0
	v_pk_mov_b32 v[120:121], 0, 0
	v_pk_mov_b32 v[122:123], 0, 0
	v_pk_mov_b32 v[124:125], 0, 0
	v_pk_mov_b32 v[126:127], 0, 0
	v_pk_mov_b32 v[116:117], 0, 0
	v_pk_mov_b32 v[118:119], 0, 0
	v_pk_mov_b32 v[104:105], 0, 0
	v_pk_mov_b32 v[106:107], 0, 0
	v_pk_mov_b32 v[88:89], 0, 0
	v_pk_mov_b32 v[90:91], 0, 0
	v_pk_mov_b32 v[80:81], 0, 0
	v_pk_mov_b32 v[82:83], 0, 0
	v_pk_mov_b32 v[72:73], 0, 0
	v_pk_mov_b32 v[74:75], 0, 0
	v_pk_mov_b32 v[64:65], 0, 0
	v_pk_mov_b32 v[66:67], 0, 0
	v_pk_mov_b32 v[60:61], 0, 0
	v_pk_mov_b32 v[62:63], 0, 0
	v_pk_mov_b32 v[52:53], 0, 0
	v_pk_mov_b32 v[54:55], 0, 0
	v_pk_mov_b32 v[44:45], 0, 0
	v_pk_mov_b32 v[46:47], 0, 0
	v_pk_mov_b32 v[36:37], 0, 0
	v_pk_mov_b32 v[38:39], 0, 0
	v_pk_mov_b32 v[28:29], 0, 0
	v_pk_mov_b32 v[30:31], 0, 0
	v_pk_mov_b32 v[20:21], 0, 0
	v_pk_mov_b32 v[22:23], 0, 0
	v_pk_mov_b32 v[12:13], 0, 0
	v_pk_mov_b32 v[14:15], 0, 0
	v_pk_mov_b32 v[4:5], 0, 0
	v_pk_mov_b32 v[6:7], 0, 0
	v_pk_mov_b32 v[56:57], 0, 0
	v_pk_mov_b32 v[58:59], 0, 0
	v_pk_mov_b32 v[48:49], 0, 0
	v_pk_mov_b32 v[50:51], 0, 0
	v_pk_mov_b32 v[40:41], 0, 0
	v_pk_mov_b32 v[42:43], 0, 0
	v_pk_mov_b32 v[32:33], 0, 0
	v_pk_mov_b32 v[34:35], 0, 0
	v_pk_mov_b32 v[24:25], 0, 0
	v_pk_mov_b32 v[26:27], 0, 0
	v_pk_mov_b32 v[16:17], 0, 0
	v_pk_mov_b32 v[18:19], 0, 0
	v_pk_mov_b32 v[8:9], 0, 0
	v_pk_mov_b32 v[10:11], 0, 0
	v_pk_mov_b32 v[0:1], 0, 0
	v_pk_mov_b32 v[2:3], 0, 0
	s_cbranch_vccnz .LBB0_1053
	s_barrier
	s_branch .LBB0_1053
.Lp7_scale:
	v_lshl_add_u32 v146, s36, 8, v151
	v_lshl_add_u32 v144, s61, 8, v153
	v_ashrrev_i32_e32 v145, 31, v144
	v_lshlrev_b64 v[144:145], 1, v[144:145]
	v_add_u32_e32 v148, 0x0, v146
	v_ashrrev_i32_e32 v149, 31, v148
	v_lshlrev_b64 v[148:149], 12, v[148:149]
	v_lshl_add_u64 v[148:149], s[20:21], 0, v[148:149]
	v_lshl_add_u64 v[148:149], v[148:149], 0, v[144:145]
	global_load_dwordx4 v[156:159], v[148:149], off
	global_load_dwordx4 v[160:163], v[148:149], off offset:256
	global_load_dwordx4 v[192:195], v[148:149], off offset:2048
	global_load_dwordx4 v[196:199], v[148:149], off offset:2304
	v_add_u32_e32 v148, 0x10, v146
	v_ashrrev_i32_e32 v149, 31, v148
	v_lshlrev_b64 v[148:149], 12, v[148:149]
	v_lshl_add_u64 v[148:149], s[20:21], 0, v[148:149]
	v_lshl_add_u64 v[148:149], v[148:149], 0, v[144:145]
	global_load_dwordx4 v[164:167], v[148:149], off
	global_load_dwordx4 v[168:171], v[148:149], off offset:256
	global_load_dwordx4 v[200:203], v[148:149], off offset:2048
	global_load_dwordx4 v[204:207], v[148:149], off offset:2304
	v_add_u32_e32 v148, 0x20, v146
	v_ashrrev_i32_e32 v149, 31, v148
	v_lshlrev_b64 v[148:149], 12, v[148:149]
	v_lshl_add_u64 v[148:149], s[20:21], 0, v[148:149]
	v_lshl_add_u64 v[148:149], v[148:149], 0, v[144:145]
	global_load_dwordx4 v[172:175], v[148:149], off
	global_load_dwordx4 v[176:179], v[148:149], off offset:256
	global_load_dwordx4 v[208:211], v[148:149], off offset:2048
	global_load_dwordx4 v[212:215], v[148:149], off offset:2304
	v_add_u32_e32 v148, 0x30, v146
	v_ashrrev_i32_e32 v149, 31, v148
	v_lshlrev_b64 v[148:149], 12, v[148:149]
	v_lshl_add_u64 v[148:149], s[20:21], 0, v[148:149]
	v_lshl_add_u64 v[148:149], v[148:149], 0, v[144:145]
	global_load_dwordx4 v[180:183], v[148:149], off
	global_load_dwordx4 v[188:191], v[148:149], off offset:256
	global_load_dwordx4 v[216:219], v[148:149], off offset:2048
	global_load_dwordx4 v[220:223], v[148:149], off offset:2304
	s_waitcnt vmcnt(13)
	v_lshlrev_b32_e32 v224, 16, v192
	v_and_b32_e32 v225, 0xffff0000, v192
	v_lshlrev_b32_e32 v226, 16, v193
	v_and_b32_e32 v227, 0xffff0000, v193
	v_lshlrev_b32_e32 v228, 16, v194
	v_and_b32_e32 v229, 0xffff0000, v194
	v_lshlrev_b32_e32 v230, 16, v195
	v_and_b32_e32 v231, 0xffff0000, v195
	v_max_f32_e32 v224, 0x21800000, v224
	v_max_f32_e32 v225, 0x21800000, v225
	v_max_f32_e32 v226, 0x21800000, v226
	v_max_f32_e32 v227, 0x21800000, v227
	v_max_f32_e32 v228, 0x21800000, v228
	v_max_f32_e32 v229, 0x21800000, v229
	v_max_f32_e32 v230, 0x21800000, v230
	v_max_f32_e32 v231, 0x21800000, v231
	v_rcp_f32_e32 v224, v224
	v_rcp_f32_e32 v225, v225
	v_rcp_f32_e32 v226, v226
	v_rcp_f32_e32 v227, v227
	v_rcp_f32_e32 v228, v228
	v_rcp_f32_e32 v229, v229
	v_rcp_f32_e32 v230, v230
	v_rcp_f32_e32 v231, v231
	v_lshlrev_b32_e32 v232, 16, v156
	v_and_b32_e32 v233, 0xffff0000, v156
	v_lshlrev_b32_e32 v234, 16, v157
	v_and_b32_e32 v235, 0xffff0000, v157
	v_lshlrev_b32_e32 v236, 16, v158
	v_and_b32_e32 v237, 0xffff0000, v158
	v_lshlrev_b32_e32 v238, 16, v159
	v_and_b32_e32 v239, 0xffff0000, v159
	v_pk_mul_f32 v[232:233], v[232:233], v[224:225]
	v_pk_mul_f32 v[234:235], v[234:235], v[226:227]
	v_pk_mul_f32 v[236:237], v[236:237], v[228:229]
	v_pk_mul_f32 v[238:239], v[238:239], v[230:231]
	v_pk_mul_f32 v[108:109], v[108:109], v[232:233]
	v_pk_mul_f32 v[110:111], v[110:111], v[234:235]
	v_pk_mul_f32 v[112:113], v[112:113], v[236:237]
	v_pk_mul_f32 v[114:115], v[114:115], v[238:239]
	s_waitcnt vmcnt(12)
	v_lshlrev_b32_e32 v224, 16, v196
	v_and_b32_e32 v225, 0xffff0000, v196
	v_lshlrev_b32_e32 v226, 16, v197
	v_and_b32_e32 v227, 0xffff0000, v197
	v_lshlrev_b32_e32 v228, 16, v198
	v_and_b32_e32 v229, 0xffff0000, v198
	v_lshlrev_b32_e32 v230, 16, v199
	v_and_b32_e32 v231, 0xffff0000, v199
	v_max_f32_e32 v224, 0x21800000, v224
	v_max_f32_e32 v225, 0x21800000, v225
	v_max_f32_e32 v226, 0x21800000, v226
	v_max_f32_e32 v227, 0x21800000, v227
	v_max_f32_e32 v228, 0x21800000, v228
	v_max_f32_e32 v229, 0x21800000, v229
	v_max_f32_e32 v230, 0x21800000, v230
	v_max_f32_e32 v231, 0x21800000, v231
	v_rcp_f32_e32 v224, v224
	v_rcp_f32_e32 v225, v225
	v_rcp_f32_e32 v226, v226
	v_rcp_f32_e32 v227, v227
	v_rcp_f32_e32 v228, v228
	v_rcp_f32_e32 v229, v229
	v_rcp_f32_e32 v230, v230
	v_rcp_f32_e32 v231, v231
	v_lshlrev_b32_e32 v232, 16, v160
	v_and_b32_e32 v233, 0xffff0000, v160
	v_lshlrev_b32_e32 v234, 16, v161
	v_and_b32_e32 v235, 0xffff0000, v161
	v_lshlrev_b32_e32 v236, 16, v162
	v_and_b32_e32 v237, 0xffff0000, v162
	v_lshlrev_b32_e32 v238, 16, v163
	v_and_b32_e32 v239, 0xffff0000, v163
	v_pk_mul_f32 v[232:233], v[232:233], v[224:225]
	v_pk_mul_f32 v[234:235], v[234:235], v[226:227]
	v_pk_mul_f32 v[236:237], v[236:237], v[228:229]
	v_pk_mul_f32 v[238:239], v[238:239], v[230:231]
	v_pk_mul_f32 v[120:121], v[120:121], v[232:233]
	v_pk_mul_f32 v[122:123], v[122:123], v[234:235]
	v_pk_mul_f32 v[124:125], v[124:125], v[236:237]
	v_pk_mul_f32 v[126:127], v[126:127], v[238:239]
	s_waitcnt vmcnt(9)
	v_lshlrev_b32_e32 v224, 16, v200
	v_and_b32_e32 v225, 0xffff0000, v200
	v_lshlrev_b32_e32 v226, 16, v201
	v_and_b32_e32 v227, 0xffff0000, v201
	v_lshlrev_b32_e32 v228, 16, v202
	v_and_b32_e32 v229, 0xffff0000, v202
	v_lshlrev_b32_e32 v230, 16, v203
	v_and_b32_e32 v231, 0xffff0000, v203
	v_max_f32_e32 v224, 0x21800000, v224
	v_max_f32_e32 v225, 0x21800000, v225
	v_max_f32_e32 v226, 0x21800000, v226
	v_max_f32_e32 v227, 0x21800000, v227
	v_max_f32_e32 v228, 0x21800000, v228
	v_max_f32_e32 v229, 0x21800000, v229
	v_max_f32_e32 v230, 0x21800000, v230
	v_max_f32_e32 v231, 0x21800000, v231
	v_rcp_f32_e32 v224, v224
	v_rcp_f32_e32 v225, v225
	v_rcp_f32_e32 v226, v226
	v_rcp_f32_e32 v227, v227
	v_rcp_f32_e32 v228, v228
	v_rcp_f32_e32 v229, v229
	v_rcp_f32_e32 v230, v230
	v_rcp_f32_e32 v231, v231
	v_lshlrev_b32_e32 v232, 16, v164
	v_and_b32_e32 v233, 0xffff0000, v164
	v_lshlrev_b32_e32 v234, 16, v165
	v_and_b32_e32 v235, 0xffff0000, v165
	v_lshlrev_b32_e32 v236, 16, v166
	v_and_b32_e32 v237, 0xffff0000, v166
	v_lshlrev_b32_e32 v238, 16, v167
	v_and_b32_e32 v239, 0xffff0000, v167
	v_pk_mul_f32 v[232:233], v[232:233], v[224:225]
	v_pk_mul_f32 v[234:235], v[234:235], v[226:227]
	v_pk_mul_f32 v[236:237], v[236:237], v[228:229]
	v_pk_mul_f32 v[238:239], v[238:239], v[230:231]
	v_pk_mul_f32 v[96:97], v[96:97], v[232:233]
	v_pk_mul_f32 v[98:99], v[98:99], v[234:235]
	v_pk_mul_f32 v[100:101], v[100:101], v[236:237]
	v_pk_mul_f32 v[102:103], v[102:103], v[238:239]
	s_waitcnt vmcnt(8)
	v_lshlrev_b32_e32 v224, 16, v204
	v_and_b32_e32 v225, 0xffff0000, v204
	v_lshlrev_b32_e32 v226, 16, v205
	v_and_b32_e32 v227, 0xffff0000, v205
	v_lshlrev_b32_e32 v228, 16, v206
	v_and_b32_e32 v229, 0xffff0000, v206
	v_lshlrev_b32_e32 v230, 16, v207
	v_and_b32_e32 v231, 0xffff0000, v207
	v_max_f32_e32 v224, 0x21800000, v224
	v_max_f32_e32 v225, 0x21800000, v225
	v_max_f32_e32 v226, 0x21800000, v226
	v_max_f32_e32 v227, 0x21800000, v227
	v_max_f32_e32 v228, 0x21800000, v228
	v_max_f32_e32 v229, 0x21800000, v229
	v_max_f32_e32 v230, 0x21800000, v230
	v_max_f32_e32 v231, 0x21800000, v231
	v_rcp_f32_e32 v224, v224
	v_rcp_f32_e32 v225, v225
	v_rcp_f32_e32 v226, v226
	v_rcp_f32_e32 v227, v227
	v_rcp_f32_e32 v228, v228
	v_rcp_f32_e32 v229, v229
	v_rcp_f32_e32 v230, v230
	v_rcp_f32_e32 v231, v231
	v_lshlrev_b32_e32 v232, 16, v168
	v_and_b32_e32 v233, 0xffff0000, v168
	v_lshlrev_b32_e32 v234, 16, v169
	v_and_b32_e32 v235, 0xffff0000, v169
	v_lshlrev_b32_e32 v236, 16, v170
	v_and_b32_e32 v237, 0xffff0000, v170
	v_lshlrev_b32_e32 v238, 16, v171
	v_and_b32_e32 v239, 0xffff0000, v171
	v_pk_mul_f32 v[232:233], v[232:233], v[224:225]
	v_pk_mul_f32 v[234:235], v[234:235], v[226:227]
	v_pk_mul_f32 v[236:237], v[236:237], v[228:229]
	v_pk_mul_f32 v[238:239], v[238:239], v[230:231]
	v_pk_mul_f32 v[116:117], v[116:117], v[232:233]
	v_pk_mul_f32 v[118:119], v[118:119], v[234:235]
	v_pk_mul_f32 v[104:105], v[104:105], v[236:237]
	v_pk_mul_f32 v[106:107], v[106:107], v[238:239]
	s_waitcnt vmcnt(5)
	v_lshlrev_b32_e32 v224, 16, v208
	v_and_b32_e32 v225, 0xffff0000, v208
	v_lshlrev_b32_e32 v226, 16, v209
	v_and_b32_e32 v227, 0xffff0000, v209
	v_lshlrev_b32_e32 v228, 16, v210
	v_and_b32_e32 v229, 0xffff0000, v210
	v_lshlrev_b32_e32 v230, 16, v211
	v_and_b32_e32 v231, 0xffff0000, v211
	v_max_f32_e32 v224, 0x21800000, v224
	v_max_f32_e32 v225, 0x21800000, v225
	v_max_f32_e32 v226, 0x21800000, v226
	v_max_f32_e32 v227, 0x21800000, v227
	v_max_f32_e32 v228, 0x21800000, v228
	v_max_f32_e32 v229, 0x21800000, v229
	v_max_f32_e32 v230, 0x21800000, v230
	v_max_f32_e32 v231, 0x21800000, v231
	v_rcp_f32_e32 v224, v224
	v_rcp_f32_e32 v225, v225
	v_rcp_f32_e32 v226, v226
	v_rcp_f32_e32 v227, v227
	v_rcp_f32_e32 v228, v228
	v_rcp_f32_e32 v229, v229
	v_rcp_f32_e32 v230, v230
	v_rcp_f32_e32 v231, v231
	v_lshlrev_b32_e32 v232, 16, v172
	v_and_b32_e32 v233, 0xffff0000, v172
	v_lshlrev_b32_e32 v234, 16, v173
	v_and_b32_e32 v235, 0xffff0000, v173
	v_lshlrev_b32_e32 v236, 16, v174
	v_and_b32_e32 v237, 0xffff0000, v174
	v_lshlrev_b32_e32 v238, 16, v175
	v_and_b32_e32 v239, 0xffff0000, v175
	v_pk_mul_f32 v[232:233], v[232:233], v[224:225]
	v_pk_mul_f32 v[234:235], v[234:235], v[226:227]
	v_pk_mul_f32 v[236:237], v[236:237], v[228:229]
	v_pk_mul_f32 v[238:239], v[238:239], v[230:231]
	v_pk_mul_f32 v[92:93], v[92:93], v[232:233]
	v_pk_mul_f32 v[94:95], v[94:95], v[234:235]
	v_pk_mul_f32 v[84:85], v[84:85], v[236:237]
	v_pk_mul_f32 v[86:87], v[86:87], v[238:239]
	s_waitcnt vmcnt(4)
	v_lshlrev_b32_e32 v224, 16, v212
	v_and_b32_e32 v225, 0xffff0000, v212
	v_lshlrev_b32_e32 v226, 16, v213
	v_and_b32_e32 v227, 0xffff0000, v213
	v_lshlrev_b32_e32 v228, 16, v214
	v_and_b32_e32 v229, 0xffff0000, v214
	v_lshlrev_b32_e32 v230, 16, v215
	v_and_b32_e32 v231, 0xffff0000, v215
	v_max_f32_e32 v224, 0x21800000, v224
	v_max_f32_e32 v225, 0x21800000, v225
	v_max_f32_e32 v226, 0x21800000, v226
	v_max_f32_e32 v227, 0x21800000, v227
	v_max_f32_e32 v228, 0x21800000, v228
	v_max_f32_e32 v229, 0x21800000, v229
	v_max_f32_e32 v230, 0x21800000, v230
	v_max_f32_e32 v231, 0x21800000, v231
	v_rcp_f32_e32 v224, v224
	v_rcp_f32_e32 v225, v225
	v_rcp_f32_e32 v226, v226
	v_rcp_f32_e32 v227, v227
	v_rcp_f32_e32 v228, v228
	v_rcp_f32_e32 v229, v229
	v_rcp_f32_e32 v230, v230
	v_rcp_f32_e32 v231, v231
	v_lshlrev_b32_e32 v232, 16, v176
	v_and_b32_e32 v233, 0xffff0000, v176
	v_lshlrev_b32_e32 v234, 16, v177
	v_and_b32_e32 v235, 0xffff0000, v177
	v_lshlrev_b32_e32 v236, 16, v178
	v_and_b32_e32 v237, 0xffff0000, v178
	v_lshlrev_b32_e32 v238, 16, v179
	v_and_b32_e32 v239, 0xffff0000, v179
	v_pk_mul_f32 v[232:233], v[232:233], v[224:225]
	v_pk_mul_f32 v[234:235], v[234:235], v[226:227]
	v_pk_mul_f32 v[236:237], v[236:237], v[228:229]
	v_pk_mul_f32 v[238:239], v[238:239], v[230:231]
	v_pk_mul_f32 v[88:89], v[88:89], v[232:233]
	v_pk_mul_f32 v[90:91], v[90:91], v[234:235]
	v_pk_mul_f32 v[80:81], v[80:81], v[236:237]
	v_pk_mul_f32 v[82:83], v[82:83], v[238:239]
	s_waitcnt vmcnt(1)
	v_lshlrev_b32_e32 v224, 16, v216
	v_and_b32_e32 v225, 0xffff0000, v216
	v_lshlrev_b32_e32 v226, 16, v217
	v_and_b32_e32 v227, 0xffff0000, v217
	v_lshlrev_b32_e32 v228, 16, v218
	v_and_b32_e32 v229, 0xffff0000, v218
	v_lshlrev_b32_e32 v230, 16, v219
	v_and_b32_e32 v231, 0xffff0000, v219
	v_max_f32_e32 v224, 0x21800000, v224
	v_max_f32_e32 v225, 0x21800000, v225
	v_max_f32_e32 v226, 0x21800000, v226
	v_max_f32_e32 v227, 0x21800000, v227
	v_max_f32_e32 v228, 0x21800000, v228
	v_max_f32_e32 v229, 0x21800000, v229
	v_max_f32_e32 v230, 0x21800000, v230
	v_max_f32_e32 v231, 0x21800000, v231
	v_rcp_f32_e32 v224, v224
	v_rcp_f32_e32 v225, v225
	v_rcp_f32_e32 v226, v226
	v_rcp_f32_e32 v227, v227
	v_rcp_f32_e32 v228, v228
	v_rcp_f32_e32 v229, v229
	v_rcp_f32_e32 v230, v230
	v_rcp_f32_e32 v231, v231
	v_lshlrev_b32_e32 v232, 16, v180
	v_and_b32_e32 v233, 0xffff0000, v180
	v_lshlrev_b32_e32 v234, 16, v181
	v_and_b32_e32 v235, 0xffff0000, v181
	v_lshlrev_b32_e32 v236, 16, v182
	v_and_b32_e32 v237, 0xffff0000, v182
	v_lshlrev_b32_e32 v238, 16, v183
	v_and_b32_e32 v239, 0xffff0000, v183
	v_pk_mul_f32 v[232:233], v[232:233], v[224:225]
	v_pk_mul_f32 v[234:235], v[234:235], v[226:227]
	v_pk_mul_f32 v[236:237], v[236:237], v[228:229]
	v_pk_mul_f32 v[238:239], v[238:239], v[230:231]
	v_pk_mul_f32 v[76:77], v[76:77], v[232:233]
	v_pk_mul_f32 v[78:79], v[78:79], v[234:235]
	v_pk_mul_f32 v[68:69], v[68:69], v[236:237]
	v_pk_mul_f32 v[70:71], v[70:71], v[238:239]
	s_waitcnt vmcnt(0)
	v_lshlrev_b32_e32 v224, 16, v220
	v_and_b32_e32 v225, 0xffff0000, v220
	v_lshlrev_b32_e32 v226, 16, v221
	v_and_b32_e32 v227, 0xffff0000, v221
	v_lshlrev_b32_e32 v228, 16, v222
	v_and_b32_e32 v229, 0xffff0000, v222
	v_lshlrev_b32_e32 v230, 16, v223
	v_and_b32_e32 v231, 0xffff0000, v223
	v_max_f32_e32 v224, 0x21800000, v224
	v_max_f32_e32 v225, 0x21800000, v225
	v_max_f32_e32 v226, 0x21800000, v226
	v_max_f32_e32 v227, 0x21800000, v227
	v_max_f32_e32 v228, 0x21800000, v228
	v_max_f32_e32 v229, 0x21800000, v229
	v_max_f32_e32 v230, 0x21800000, v230
	v_max_f32_e32 v231, 0x21800000, v231
	v_rcp_f32_e32 v224, v224
	v_rcp_f32_e32 v225, v225
	v_rcp_f32_e32 v226, v226
	v_rcp_f32_e32 v227, v227
	v_rcp_f32_e32 v228, v228
	v_rcp_f32_e32 v229, v229
	v_rcp_f32_e32 v230, v230
	v_rcp_f32_e32 v231, v231
	v_lshlrev_b32_e32 v232, 16, v188
	v_and_b32_e32 v233, 0xffff0000, v188
	v_lshlrev_b32_e32 v234, 16, v189
	v_and_b32_e32 v235, 0xffff0000, v189
	v_lshlrev_b32_e32 v236, 16, v190
	v_and_b32_e32 v237, 0xffff0000, v190
	v_lshlrev_b32_e32 v238, 16, v191
	v_and_b32_e32 v239, 0xffff0000, v191
	v_pk_mul_f32 v[232:233], v[232:233], v[224:225]
	v_pk_mul_f32 v[234:235], v[234:235], v[226:227]
	v_pk_mul_f32 v[236:237], v[236:237], v[228:229]
	v_pk_mul_f32 v[238:239], v[238:239], v[230:231]
	v_pk_mul_f32 v[72:73], v[72:73], v[232:233]
	v_pk_mul_f32 v[74:75], v[74:75], v[234:235]
	v_pk_mul_f32 v[64:65], v[64:65], v[236:237]
	v_pk_mul_f32 v[66:67], v[66:67], v[238:239]
	v_add_u32_e32 v148, 0x80, v146
	v_ashrrev_i32_e32 v149, 31, v148
	v_lshlrev_b64 v[148:149], 12, v[148:149]
	v_lshl_add_u64 v[148:149], s[20:21], 0, v[148:149]
	v_lshl_add_u64 v[148:149], v[148:149], 0, v[144:145]
	global_load_dwordx4 v[156:159], v[148:149], off
	global_load_dwordx4 v[160:163], v[148:149], off offset:256
	global_load_dwordx4 v[192:195], v[148:149], off offset:2048
	global_load_dwordx4 v[196:199], v[148:149], off offset:2304
	v_add_u32_e32 v148, 0x90, v146
	v_ashrrev_i32_e32 v149, 31, v148
	v_lshlrev_b64 v[148:149], 12, v[148:149]
	v_lshl_add_u64 v[148:149], s[20:21], 0, v[148:149]
	v_lshl_add_u64 v[148:149], v[148:149], 0, v[144:145]
	global_load_dwordx4 v[164:167], v[148:149], off
	global_load_dwordx4 v[168:171], v[148:149], off offset:256
	global_load_dwordx4 v[200:203], v[148:149], off offset:2048
	global_load_dwordx4 v[204:207], v[148:149], off offset:2304
	v_add_u32_e32 v148, 0xa0, v146
	v_ashrrev_i32_e32 v149, 31, v148
	v_lshlrev_b64 v[148:149], 12, v[148:149]
	v_lshl_add_u64 v[148:149], s[20:21], 0, v[148:149]
	v_lshl_add_u64 v[148:149], v[148:149], 0, v[144:145]
	global_load_dwordx4 v[172:175], v[148:149], off
	global_load_dwordx4 v[176:179], v[148:149], off offset:256
	global_load_dwordx4 v[208:211], v[148:149], off offset:2048
	global_load_dwordx4 v[212:215], v[148:149], off offset:2304
	v_add_u32_e32 v148, 0xb0, v146
	v_ashrrev_i32_e32 v149, 31, v148
	v_lshlrev_b64 v[148:149], 12, v[148:149]
	v_lshl_add_u64 v[148:149], s[20:21], 0, v[148:149]
	v_lshl_add_u64 v[148:149], v[148:149], 0, v[144:145]
	global_load_dwordx4 v[180:183], v[148:149], off
	global_load_dwordx4 v[188:191], v[148:149], off offset:256
	global_load_dwordx4 v[216:219], v[148:149], off offset:2048
	global_load_dwordx4 v[220:223], v[148:149], off offset:2304
	s_waitcnt vmcnt(13)
	v_lshlrev_b32_e32 v224, 16, v192
	v_and_b32_e32 v225, 0xffff0000, v192
	v_lshlrev_b32_e32 v226, 16, v193
	v_and_b32_e32 v227, 0xffff0000, v193
	v_lshlrev_b32_e32 v228, 16, v194
	v_and_b32_e32 v229, 0xffff0000, v194
	v_lshlrev_b32_e32 v230, 16, v195
	v_and_b32_e32 v231, 0xffff0000, v195
	v_max_f32_e32 v224, 0x21800000, v224
	v_max_f32_e32 v225, 0x21800000, v225
	v_max_f32_e32 v226, 0x21800000, v226
	v_max_f32_e32 v227, 0x21800000, v227
	v_max_f32_e32 v228, 0x21800000, v228
	v_max_f32_e32 v229, 0x21800000, v229
	v_max_f32_e32 v230, 0x21800000, v230
	v_max_f32_e32 v231, 0x21800000, v231
	v_rcp_f32_e32 v224, v224
	v_rcp_f32_e32 v225, v225
	v_rcp_f32_e32 v226, v226
	v_rcp_f32_e32 v227, v227
	v_rcp_f32_e32 v228, v228
	v_rcp_f32_e32 v229, v229
	v_rcp_f32_e32 v230, v230
	v_rcp_f32_e32 v231, v231
	v_lshlrev_b32_e32 v232, 16, v156
	v_and_b32_e32 v233, 0xffff0000, v156
	v_lshlrev_b32_e32 v234, 16, v157
	v_and_b32_e32 v235, 0xffff0000, v157
	v_lshlrev_b32_e32 v236, 16, v158
	v_and_b32_e32 v237, 0xffff0000, v158
	v_lshlrev_b32_e32 v238, 16, v159
	v_and_b32_e32 v239, 0xffff0000, v159
	v_pk_mul_f32 v[232:233], v[232:233], v[224:225]
	v_pk_mul_f32 v[234:235], v[234:235], v[226:227]
	v_pk_mul_f32 v[236:237], v[236:237], v[228:229]
	v_pk_mul_f32 v[238:239], v[238:239], v[230:231]
	v_pk_mul_f32 v[60:61], v[60:61], v[232:233]
	v_pk_mul_f32 v[62:63], v[62:63], v[234:235]
	v_pk_mul_f32 v[52:53], v[52:53], v[236:237]
	v_pk_mul_f32 v[54:55], v[54:55], v[238:239]
	s_waitcnt vmcnt(12)
	v_lshlrev_b32_e32 v224, 16, v196
	v_and_b32_e32 v225, 0xffff0000, v196
	v_lshlrev_b32_e32 v226, 16, v197
	v_and_b32_e32 v227, 0xffff0000, v197
	v_lshlrev_b32_e32 v228, 16, v198
	v_and_b32_e32 v229, 0xffff0000, v198
	v_lshlrev_b32_e32 v230, 16, v199
	v_and_b32_e32 v231, 0xffff0000, v199
	v_max_f32_e32 v224, 0x21800000, v224
	v_max_f32_e32 v225, 0x21800000, v225
	v_max_f32_e32 v226, 0x21800000, v226
	v_max_f32_e32 v227, 0x21800000, v227
	v_max_f32_e32 v228, 0x21800000, v228
	v_max_f32_e32 v229, 0x21800000, v229
	v_max_f32_e32 v230, 0x21800000, v230
	v_max_f32_e32 v231, 0x21800000, v231
	v_rcp_f32_e32 v224, v224
	v_rcp_f32_e32 v225, v225
	v_rcp_f32_e32 v226, v226
	v_rcp_f32_e32 v227, v227
	v_rcp_f32_e32 v228, v228
	v_rcp_f32_e32 v229, v229
	v_rcp_f32_e32 v230, v230
	v_rcp_f32_e32 v231, v231
	v_lshlrev_b32_e32 v232, 16, v160
	v_and_b32_e32 v233, 0xffff0000, v160
	v_lshlrev_b32_e32 v234, 16, v161
	v_and_b32_e32 v235, 0xffff0000, v161
	v_lshlrev_b32_e32 v236, 16, v162
	v_and_b32_e32 v237, 0xffff0000, v162
	v_lshlrev_b32_e32 v238, 16, v163
	v_and_b32_e32 v239, 0xffff0000, v163
	v_pk_mul_f32 v[232:233], v[232:233], v[224:225]
	v_pk_mul_f32 v[234:235], v[234:235], v[226:227]
	v_pk_mul_f32 v[236:237], v[236:237], v[228:229]
	v_pk_mul_f32 v[238:239], v[238:239], v[230:231]
	v_pk_mul_f32 v[56:57], v[56:57], v[232:233]
	v_pk_mul_f32 v[58:59], v[58:59], v[234:235]
	v_pk_mul_f32 v[48:49], v[48:49], v[236:237]
	v_pk_mul_f32 v[50:51], v[50:51], v[238:239]
	s_waitcnt vmcnt(9)
	v_lshlrev_b32_e32 v224, 16, v200
	v_and_b32_e32 v225, 0xffff0000, v200
	v_lshlrev_b32_e32 v226, 16, v201
	v_and_b32_e32 v227, 0xffff0000, v201
	v_lshlrev_b32_e32 v228, 16, v202
	v_and_b32_e32 v229, 0xffff0000, v202
	v_lshlrev_b32_e32 v230, 16, v203
	v_and_b32_e32 v231, 0xffff0000, v203
	v_max_f32_e32 v224, 0x21800000, v224
	v_max_f32_e32 v225, 0x21800000, v225
	v_max_f32_e32 v226, 0x21800000, v226
	v_max_f32_e32 v227, 0x21800000, v227
	v_max_f32_e32 v228, 0x21800000, v228
	v_max_f32_e32 v229, 0x21800000, v229
	v_max_f32_e32 v230, 0x21800000, v230
	v_max_f32_e32 v231, 0x21800000, v231
	v_rcp_f32_e32 v224, v224
	v_rcp_f32_e32 v225, v225
	v_rcp_f32_e32 v226, v226
	v_rcp_f32_e32 v227, v227
	v_rcp_f32_e32 v228, v228
	v_rcp_f32_e32 v229, v229
	v_rcp_f32_e32 v230, v230
	v_rcp_f32_e32 v231, v231
	v_lshlrev_b32_e32 v232, 16, v164
	v_and_b32_e32 v233, 0xffff0000, v164
	v_lshlrev_b32_e32 v234, 16, v165
	v_and_b32_e32 v235, 0xffff0000, v165
	v_lshlrev_b32_e32 v236, 16, v166
	v_and_b32_e32 v237, 0xffff0000, v166
	v_lshlrev_b32_e32 v238, 16, v167
	v_and_b32_e32 v239, 0xffff0000, v167
	v_pk_mul_f32 v[232:233], v[232:233], v[224:225]
	v_pk_mul_f32 v[234:235], v[234:235], v[226:227]
	v_pk_mul_f32 v[236:237], v[236:237], v[228:229]
	v_pk_mul_f32 v[238:239], v[238:239], v[230:231]
	v_pk_mul_f32 v[44:45], v[44:45], v[232:233]
	v_pk_mul_f32 v[46:47], v[46:47], v[234:235]
	v_pk_mul_f32 v[36:37], v[36:37], v[236:237]
	v_pk_mul_f32 v[38:39], v[38:39], v[238:239]
	s_waitcnt vmcnt(8)
	v_lshlrev_b32_e32 v224, 16, v204
	v_and_b32_e32 v225, 0xffff0000, v204
	v_lshlrev_b32_e32 v226, 16, v205
	v_and_b32_e32 v227, 0xffff0000, v205
	v_lshlrev_b32_e32 v228, 16, v206
	v_and_b32_e32 v229, 0xffff0000, v206
	v_lshlrev_b32_e32 v230, 16, v207
	v_and_b32_e32 v231, 0xffff0000, v207
	v_max_f32_e32 v224, 0x21800000, v224
	v_max_f32_e32 v225, 0x21800000, v225
	v_max_f32_e32 v226, 0x21800000, v226
	v_max_f32_e32 v227, 0x21800000, v227
	v_max_f32_e32 v228, 0x21800000, v228
	v_max_f32_e32 v229, 0x21800000, v229
	v_max_f32_e32 v230, 0x21800000, v230
	v_max_f32_e32 v231, 0x21800000, v231
	v_rcp_f32_e32 v224, v224
	v_rcp_f32_e32 v225, v225
	v_rcp_f32_e32 v226, v226
	v_rcp_f32_e32 v227, v227
	v_rcp_f32_e32 v228, v228
	v_rcp_f32_e32 v229, v229
	v_rcp_f32_e32 v230, v230
	v_rcp_f32_e32 v231, v231
	v_lshlrev_b32_e32 v232, 16, v168
	v_and_b32_e32 v233, 0xffff0000, v168
	v_lshlrev_b32_e32 v234, 16, v169
	v_and_b32_e32 v235, 0xffff0000, v169
	v_lshlrev_b32_e32 v236, 16, v170
	v_and_b32_e32 v237, 0xffff0000, v170
	v_lshlrev_b32_e32 v238, 16, v171
	v_and_b32_e32 v239, 0xffff0000, v171
	v_pk_mul_f32 v[232:233], v[232:233], v[224:225]
	v_pk_mul_f32 v[234:235], v[234:235], v[226:227]
	v_pk_mul_f32 v[236:237], v[236:237], v[228:229]
	v_pk_mul_f32 v[238:239], v[238:239], v[230:231]
	v_pk_mul_f32 v[40:41], v[40:41], v[232:233]
	v_pk_mul_f32 v[42:43], v[42:43], v[234:235]
	v_pk_mul_f32 v[32:33], v[32:33], v[236:237]
	v_pk_mul_f32 v[34:35], v[34:35], v[238:239]
	s_waitcnt vmcnt(5)
	v_lshlrev_b32_e32 v224, 16, v208
	v_and_b32_e32 v225, 0xffff0000, v208
	v_lshlrev_b32_e32 v226, 16, v209
	v_and_b32_e32 v227, 0xffff0000, v209
	v_lshlrev_b32_e32 v228, 16, v210
	v_and_b32_e32 v229, 0xffff0000, v210
	v_lshlrev_b32_e32 v230, 16, v211
	v_and_b32_e32 v231, 0xffff0000, v211
	v_max_f32_e32 v224, 0x21800000, v224
	v_max_f32_e32 v225, 0x21800000, v225
	v_max_f32_e32 v226, 0x21800000, v226
	v_max_f32_e32 v227, 0x21800000, v227
	v_max_f32_e32 v228, 0x21800000, v228
	v_max_f32_e32 v229, 0x21800000, v229
	v_max_f32_e32 v230, 0x21800000, v230
	v_max_f32_e32 v231, 0x21800000, v231
	v_rcp_f32_e32 v224, v224
	v_rcp_f32_e32 v225, v225
	v_rcp_f32_e32 v226, v226
	v_rcp_f32_e32 v227, v227
	v_rcp_f32_e32 v228, v228
	v_rcp_f32_e32 v229, v229
	v_rcp_f32_e32 v230, v230
	v_rcp_f32_e32 v231, v231
	v_lshlrev_b32_e32 v232, 16, v172
	v_and_b32_e32 v233, 0xffff0000, v172
	v_lshlrev_b32_e32 v234, 16, v173
	v_and_b32_e32 v235, 0xffff0000, v173
	v_lshlrev_b32_e32 v236, 16, v174
	v_and_b32_e32 v237, 0xffff0000, v174
	v_lshlrev_b32_e32 v238, 16, v175
	v_and_b32_e32 v239, 0xffff0000, v175
	v_pk_mul_f32 v[232:233], v[232:233], v[224:225]
	v_pk_mul_f32 v[234:235], v[234:235], v[226:227]
	v_pk_mul_f32 v[236:237], v[236:237], v[228:229]
	v_pk_mul_f32 v[238:239], v[238:239], v[230:231]
	v_pk_mul_f32 v[28:29], v[28:29], v[232:233]
	v_pk_mul_f32 v[30:31], v[30:31], v[234:235]
	v_pk_mul_f32 v[20:21], v[20:21], v[236:237]
	v_pk_mul_f32 v[22:23], v[22:23], v[238:239]
	s_waitcnt vmcnt(4)
	v_lshlrev_b32_e32 v224, 16, v212
	v_and_b32_e32 v225, 0xffff0000, v212
	v_lshlrev_b32_e32 v226, 16, v213
	v_and_b32_e32 v227, 0xffff0000, v213
	v_lshlrev_b32_e32 v228, 16, v214
	v_and_b32_e32 v229, 0xffff0000, v214
	v_lshlrev_b32_e32 v230, 16, v215
	v_and_b32_e32 v231, 0xffff0000, v215
	v_max_f32_e32 v224, 0x21800000, v224
	v_max_f32_e32 v225, 0x21800000, v225
	v_max_f32_e32 v226, 0x21800000, v226
	v_max_f32_e32 v227, 0x21800000, v227
	v_max_f32_e32 v228, 0x21800000, v228
	v_max_f32_e32 v229, 0x21800000, v229
	v_max_f32_e32 v230, 0x21800000, v230
	v_max_f32_e32 v231, 0x21800000, v231
	v_rcp_f32_e32 v224, v224
	v_rcp_f32_e32 v225, v225
	v_rcp_f32_e32 v226, v226
	v_rcp_f32_e32 v227, v227
	v_rcp_f32_e32 v228, v228
	v_rcp_f32_e32 v229, v229
	v_rcp_f32_e32 v230, v230
	v_rcp_f32_e32 v231, v231
	v_lshlrev_b32_e32 v232, 16, v176
	v_and_b32_e32 v233, 0xffff0000, v176
	v_lshlrev_b32_e32 v234, 16, v177
	v_and_b32_e32 v235, 0xffff0000, v177
	v_lshlrev_b32_e32 v236, 16, v178
	v_and_b32_e32 v237, 0xffff0000, v178
	v_lshlrev_b32_e32 v238, 16, v179
	v_and_b32_e32 v239, 0xffff0000, v179
	v_pk_mul_f32 v[232:233], v[232:233], v[224:225]
	v_pk_mul_f32 v[234:235], v[234:235], v[226:227]
	v_pk_mul_f32 v[236:237], v[236:237], v[228:229]
	v_pk_mul_f32 v[238:239], v[238:239], v[230:231]
	v_pk_mul_f32 v[24:25], v[24:25], v[232:233]
	v_pk_mul_f32 v[26:27], v[26:27], v[234:235]
	v_pk_mul_f32 v[16:17], v[16:17], v[236:237]
	v_pk_mul_f32 v[18:19], v[18:19], v[238:239]
	s_waitcnt vmcnt(1)
	v_lshlrev_b32_e32 v224, 16, v216
	v_and_b32_e32 v225, 0xffff0000, v216
	v_lshlrev_b32_e32 v226, 16, v217
	v_and_b32_e32 v227, 0xffff0000, v217
	v_lshlrev_b32_e32 v228, 16, v218
	v_and_b32_e32 v229, 0xffff0000, v218
	v_lshlrev_b32_e32 v230, 16, v219
	v_and_b32_e32 v231, 0xffff0000, v219
	v_max_f32_e32 v224, 0x21800000, v224
	v_max_f32_e32 v225, 0x21800000, v225
	v_max_f32_e32 v226, 0x21800000, v226
	v_max_f32_e32 v227, 0x21800000, v227
	v_max_f32_e32 v228, 0x21800000, v228
	v_max_f32_e32 v229, 0x21800000, v229
	v_max_f32_e32 v230, 0x21800000, v230
	v_max_f32_e32 v231, 0x21800000, v231
	v_rcp_f32_e32 v224, v224
	v_rcp_f32_e32 v225, v225
	v_rcp_f32_e32 v226, v226
	v_rcp_f32_e32 v227, v227
	v_rcp_f32_e32 v228, v228
	v_rcp_f32_e32 v229, v229
	v_rcp_f32_e32 v230, v230
	v_rcp_f32_e32 v231, v231
	v_lshlrev_b32_e32 v232, 16, v180
	v_and_b32_e32 v233, 0xffff0000, v180
	v_lshlrev_b32_e32 v234, 16, v181
	v_and_b32_e32 v235, 0xffff0000, v181
	v_lshlrev_b32_e32 v236, 16, v182
	v_and_b32_e32 v237, 0xffff0000, v182
	v_lshlrev_b32_e32 v238, 16, v183
	v_and_b32_e32 v239, 0xffff0000, v183
	v_pk_mul_f32 v[232:233], v[232:233], v[224:225]
	v_pk_mul_f32 v[234:235], v[234:235], v[226:227]
	v_pk_mul_f32 v[236:237], v[236:237], v[228:229]
	v_pk_mul_f32 v[238:239], v[238:239], v[230:231]
	v_pk_mul_f32 v[12:13], v[12:13], v[232:233]
	v_pk_mul_f32 v[14:15], v[14:15], v[234:235]
	v_pk_mul_f32 v[4:5], v[4:5], v[236:237]
	v_pk_mul_f32 v[6:7], v[6:7], v[238:239]
	s_waitcnt vmcnt(0)
	v_lshlrev_b32_e32 v224, 16, v220
	v_and_b32_e32 v225, 0xffff0000, v220
	v_lshlrev_b32_e32 v226, 16, v221
	v_and_b32_e32 v227, 0xffff0000, v221
	v_lshlrev_b32_e32 v228, 16, v222
	v_and_b32_e32 v229, 0xffff0000, v222
	v_lshlrev_b32_e32 v230, 16, v223
	v_and_b32_e32 v231, 0xffff0000, v223
	v_max_f32_e32 v224, 0x21800000, v224
	v_max_f32_e32 v225, 0x21800000, v225
	v_max_f32_e32 v226, 0x21800000, v226
	v_max_f32_e32 v227, 0x21800000, v227
	v_max_f32_e32 v228, 0x21800000, v228
	v_max_f32_e32 v229, 0x21800000, v229
	v_max_f32_e32 v230, 0x21800000, v230
	v_max_f32_e32 v231, 0x21800000, v231
	v_rcp_f32_e32 v224, v224
	v_rcp_f32_e32 v225, v225
	v_rcp_f32_e32 v226, v226
	v_rcp_f32_e32 v227, v227
	v_rcp_f32_e32 v228, v228
	v_rcp_f32_e32 v229, v229
	v_rcp_f32_e32 v230, v230
	v_rcp_f32_e32 v231, v231
	v_lshlrev_b32_e32 v232, 16, v188
	v_and_b32_e32 v233, 0xffff0000, v188
	v_lshlrev_b32_e32 v234, 16, v189
	v_and_b32_e32 v235, 0xffff0000, v189
	v_lshlrev_b32_e32 v236, 16, v190
	v_and_b32_e32 v237, 0xffff0000, v190
	v_lshlrev_b32_e32 v238, 16, v191
	v_and_b32_e32 v239, 0xffff0000, v191
	v_pk_mul_f32 v[232:233], v[232:233], v[224:225]
	v_pk_mul_f32 v[234:235], v[234:235], v[226:227]
	v_pk_mul_f32 v[236:237], v[236:237], v[228:229]
	v_pk_mul_f32 v[238:239], v[238:239], v[230:231]
	v_pk_mul_f32 v[8:9], v[8:9], v[232:233]
	v_pk_mul_f32 v[10:11], v[10:11], v[234:235]
	v_pk_mul_f32 v[0:1], v[0:1], v[236:237]
	v_pk_mul_f32 v[2:3], v[2:3], v[238:239]
	s_andn2_b64 vcc, exec, s[16:17]
	s_cbranch_vccnz .LBB0_1053
	s_barrier
	s_branch .LBB0_1053
.Lp7_force_next:
	s_mov_b64 s[4:5], exec
	s_mov_b32 s28, s36
	s_mov_b32 s60, s61
	s_branch .LBB0_1061
.LBB0_1071:
	s_waitcnt vmcnt(0)
	s_barrier
.LBB0_1072:
	s_branch .LBB0_1099
.LBB0_1099:
	s_cmp_gt_i32 s87, 8
	s_cselect_b64 s[0:1], -1, 0
	s_and_b64 s[2:3], s[6:7], s[0:1]
	s_andn2_b64 vcc, exec, s[2:3]
	s_cbranch_vccnz .LBB0_1144
	s_waitcnt vmcnt(0)
	s_waitcnt vmcnt(0) lgkmcnt(0)
	s_barrier
	s_and_saveexec_b64 s[2:3], s[90:91]
	s_cbranch_execz .LBB0_1143
	s_add_i32 s4, 0, 0x23fc0
	v_mov_b32_e32 v0, s4
	s_waitcnt vmcnt(0) expcnt(0) lgkmcnt(0)
	ds_read_b32 v2, v0
	s_add_i32 s4, 0, 0x23fc4
	v_mov_b32_e32 v0, s4
	ds_read_b32 v0, v0
	s_waitcnt lgkmcnt(1)
	v_cmp_ne_u32_e32 vcc, 0, v2
	s_cbranch_vccnz .LBB0_1114
	s_load_dwordx2 s[8:9], s[88:89], 0x4
	s_add_u32 s4, s84, 0x1000
	s_addc_u32 s5, s85, 0
	s_add_u32 s6, s84, 0x1100
	s_addc_u32 s7, s85, 0
	s_waitcnt lgkmcnt(0)
	s_mul_i32 s18, s8, s79
	s_add_u32 s8, s84, 0x1200
	s_mul_i32 s18, s18, s9
	s_addc_u32 s9, s85, 0
	s_add_u32 s10, s84, 0x1300
	s_addc_u32 s11, s85, 0
	s_mov_b32 s19, 1
	v_mov_b32_e32 v16, 0
	s_branch .LBB0_1104
